# v22 + layer-0 w_in item loads (8 masked groups of 4) issued as 32 back-to-back with counted waits; first-barrier census: 16 sc1 loads issued back-to-back instead of load/wait pairs
# speedup vs baseline: 1.0088x; 1.0008x over previous
; #define LAS __attribute__((address_space(3)))
; #define LDS_WAIT() asm volatile("s_waitcnt lgkmcnt(0)" ::: "memory")
; template <int MAP> __device__ __forceinline__ void p0_item(const float* W, int K, int N, bf16* WT, LAS float* scr, int item, int lane) {
;     const int nblk = (N + 31) / 32, kb = item / nblk, nb = item % nblk, k0 = 64 * kb, n0 = 32 * nb;
;     const int nn = n0 + (lane & 31); const bool okr = nn < N;
; #pragma unroll
;     for (int i = 0; i < 32; ++i) { const int kk = 2 * i + (lane >> 5); scr[kk * 33 + (lane & 31)] = okr ? W[(size_t)(k0 + kk) * N + nn] : 0.f; }
;     LDS_WAIT(); asm volatile("" ::: "memory");
.LBB0_135:
	s_and_b64 vcc, exec, s[36:37]
	s_cbranch_vccz .LBB0_190
	s_mul_i32 s11, s10, 0x221
	s_lshr_b32 s12, s11, 18
	s_mulk_i32 s12, 0x1e1
	s_sub_i32 s12, s10, s12
	s_lshl_b32 s10, s12, 5
	s_and_b32 s10, s10, 0xffe0
	v_or_b32_e32 v6, s10, v2
	s_movk_i32 s13, 0x3c0f
	v_cmp_lt_u32_e32 vcc, s13, v6
	s_lshr_b32 s11, s11, 12
	v_lshlrev_b32_e32 v6, 2, v6
	s_and_b32 s11, s11, 0xffc0
	v_lshl_add_u64 v[14:15], s[34:35], 0, v[6:7]
	v_mov_b32_e32 v18, 0
	v_mov_b32_e32 v19, 0
	v_mov_b32_e32 v20, 0
	v_mov_b32_e32 v21, 0
	v_mov_b32_e32 v22, 0
	v_mov_b32_e32 v23, 0
	v_mov_b32_e32 v24, 0
	v_mov_b32_e32 v25, 0
	v_mov_b32_e32 v26, 0
	v_mov_b32_e32 v27, 0
	v_mov_b32_e32 v28, 0
	v_mov_b32_e32 v29, 0
	v_mov_b32_e32 v97, 0
	v_mov_b32_e32 v98, 0
	v_mov_b32_e32 v99, 0
	v_mov_b32_e32 v100, 0
	v_mov_b32_e32 v101, 0
	v_mov_b32_e32 v102, 0
	v_mov_b32_e32 v103, 0
	v_mov_b32_e32 v104, 0
	v_mov_b32_e32 v105, 0
	v_mov_b32_e32 v106, 0
	v_mov_b32_e32 v107, 0
	v_mov_b32_e32 v108, 0
	v_mov_b32_e32 v109, 0
	v_mov_b32_e32 v110, 0
	v_mov_b32_e32 v111, 0
	v_mov_b32_e32 v112, 0
	v_mov_b32_e32 v113, 0
	v_mov_b32_e32 v114, 0
	v_mov_b32_e32 v115, 0
	v_mov_b32_e32 v116, 0
	s_mov_b64 s[30:31], exec
	s_andn2_b64 exec, exec, vcc
	s_cbranch_execz .Lp5_skip
	v_or_b32_e32 v6, s11, v3
	v_mul_u32_u24_e32 v6, 0xf040, v6
	v_lshl_add_u64 v[16:17], v[14:15], 0, v[6:7]
	global_load_dword v18, v[16:17], off
	v_or_b32_e32 v6, s11, v31
	v_mul_u32_u24_e32 v6, 0xf040, v6
	v_lshl_add_u64 v[16:17], v[14:15], 0, v[6:7]
	global_load_dword v19, v[16:17], off
	v_or_b32_e32 v6, s11, v32
	v_mul_u32_u24_e32 v6, 0xf040, v6
	v_lshl_add_u64 v[16:17], v[14:15], 0, v[6:7]
	global_load_dword v20, v[16:17], off
	v_or_b32_e32 v6, s11, v34
	v_mul_u32_u24_e32 v6, 0xf040, v6
	v_lshl_add_u64 v[16:17], v[14:15], 0, v[6:7]
	global_load_dword v21, v[16:17], off
	v_or_b32_e32 v6, s11, v35
	v_mul_u32_u24_e32 v6, 0xf040, v6
	v_lshl_add_u64 v[16:17], v[14:15], 0, v[6:7]
	global_load_dword v22, v[16:17], off
	v_or_b32_e32 v6, s11, v37
	v_mul_u32_u24_e32 v6, 0xf040, v6
	v_lshl_add_u64 v[16:17], v[14:15], 0, v[6:7]
	global_load_dword v23, v[16:17], off
	v_or_b32_e32 v6, s11, v38
	v_mul_u32_u24_e32 v6, 0xf040, v6
	v_lshl_add_u64 v[16:17], v[14:15], 0, v[6:7]
	global_load_dword v24, v[16:17], off
	v_or_b32_e32 v6, s11, v40
	v_mul_u32_u24_e32 v6, 0xf040, v6
	v_lshl_add_u64 v[16:17], v[14:15], 0, v[6:7]
	global_load_dword v25, v[16:17], off
	v_or_b32_e32 v6, s11, v41
	v_mul_u32_u24_e32 v6, 0xf040, v6
	v_lshl_add_u64 v[16:17], v[14:15], 0, v[6:7]
	global_load_dword v26, v[16:17], off
	v_or_b32_e32 v6, s11, v43
	v_mul_u32_u24_e32 v6, 0xf040, v6
	v_lshl_add_u64 v[16:17], v[14:15], 0, v[6:7]
	global_load_dword v27, v[16:17], off
	v_or_b32_e32 v6, s11, v44
	v_mul_u32_u24_e32 v6, 0xf040, v6
	v_lshl_add_u64 v[16:17], v[14:15], 0, v[6:7]
	global_load_dword v28, v[16:17], off
	v_or_b32_e32 v6, s11, v46
	v_mul_u32_u24_e32 v6, 0xf040, v6
	v_lshl_add_u64 v[16:17], v[14:15], 0, v[6:7]
	global_load_dword v29, v[16:17], off
	v_or_b32_e32 v6, s11, v47
	v_mul_u32_u24_e32 v6, 0xf040, v6
	v_lshl_add_u64 v[16:17], v[14:15], 0, v[6:7]
	global_load_dword v97, v[16:17], off
	v_or_b32_e32 v6, s11, v49
	v_mul_u32_u24_e32 v6, 0xf040, v6
	v_lshl_add_u64 v[16:17], v[14:15], 0, v[6:7]
	global_load_dword v98, v[16:17], off
	v_or_b32_e32 v6, s11, v50
	v_mul_u32_u24_e32 v6, 0xf040, v6
	v_lshl_add_u64 v[16:17], v[14:15], 0, v[6:7]
	global_load_dword v99, v[16:17], off
	v_or_b32_e32 v6, s11, v52
	v_mul_u32_u24_e32 v6, 0xf040, v6
	v_lshl_add_u64 v[16:17], v[14:15], 0, v[6:7]
	global_load_dword v100, v[16:17], off
	v_or_b32_e32 v6, s11, v53
	v_mul_u32_u24_e32 v6, 0xf040, v6
	v_lshl_add_u64 v[16:17], v[14:15], 0, v[6:7]
	global_load_dword v101, v[16:17], off
	v_or_b32_e32 v6, s11, v55
	v_mul_u32_u24_e32 v6, 0xf040, v6
	v_lshl_add_u64 v[16:17], v[14:15], 0, v[6:7]
	global_load_dword v102, v[16:17], off
	v_or_b32_e32 v6, s11, v56
	v_mul_u32_u24_e32 v6, 0xf040, v6
	v_lshl_add_u64 v[16:17], v[14:15], 0, v[6:7]
	global_load_dword v103, v[16:17], off
	v_or_b32_e32 v6, s11, v76
	v_mul_u32_u24_e32 v6, 0xf040, v6
	v_lshl_add_u64 v[16:17], v[14:15], 0, v[6:7]
	global_load_dword v104, v[16:17], off
	v_or_b32_e32 v6, s11, v77
	v_mul_u32_u24_e32 v6, 0xf040, v6
	v_lshl_add_u64 v[16:17], v[14:15], 0, v[6:7]
	global_load_dword v105, v[16:17], off
	v_or_b32_e32 v6, s11, v78
	v_mul_u32_u24_e32 v6, 0xf040, v6
	v_lshl_add_u64 v[16:17], v[14:15], 0, v[6:7]
	global_load_dword v106, v[16:17], off
	v_or_b32_e32 v6, s11, v79
	v_mul_u32_u24_e32 v6, 0xf040, v6
	v_lshl_add_u64 v[16:17], v[14:15], 0, v[6:7]
	global_load_dword v107, v[16:17], off
	v_or_b32_e32 v6, s11, v80
	v_mul_u32_u24_e32 v6, 0xf040, v6
	v_lshl_add_u64 v[16:17], v[14:15], 0, v[6:7]
	global_load_dword v108, v[16:17], off
	v_or_b32_e32 v6, s11, v81
	v_mul_u32_u24_e32 v6, 0xf040, v6
	v_lshl_add_u64 v[16:17], v[14:15], 0, v[6:7]
	global_load_dword v109, v[16:17], off
	v_or_b32_e32 v6, s11, v82
	v_mul_u32_u24_e32 v6, 0xf040, v6
	v_lshl_add_u64 v[16:17], v[14:15], 0, v[6:7]
	global_load_dword v110, v[16:17], off
	v_or_b32_e32 v6, s11, v83
	v_mul_u32_u24_e32 v6, 0xf040, v6
	v_lshl_add_u64 v[16:17], v[14:15], 0, v[6:7]
	global_load_dword v111, v[16:17], off
	v_or_b32_e32 v6, s11, v84
	v_mul_u32_u24_e32 v6, 0xf040, v6
	v_lshl_add_u64 v[16:17], v[14:15], 0, v[6:7]
	global_load_dword v112, v[16:17], off
	v_or_b32_e32 v6, s11, v85
	v_mul_u32_u24_e32 v6, 0xf040, v6
	v_lshl_add_u64 v[16:17], v[14:15], 0, v[6:7]
	global_load_dword v113, v[16:17], off
	v_or_b32_e32 v6, s11, v86
	v_mul_u32_u24_e32 v6, 0xf040, v6
	v_lshl_add_u64 v[16:17], v[14:15], 0, v[6:7]
	global_load_dword v114, v[16:17], off
	v_or_b32_e32 v6, s11, v87
	v_mul_u32_u24_e32 v6, 0xf040, v6
	v_lshl_add_u64 v[16:17], v[14:15], 0, v[6:7]
	global_load_dword v115, v[16:17], off
	v_or_b32_e32 v6, s11, v88
	v_mul_u32_u24_e32 v6, 0xf040, v6
	v_lshl_add_u64 v[16:17], v[14:15], 0, v[6:7]
	global_load_dword v116, v[16:17], off
; #define GAS __attribute__((address_space(1)))
; #define LAS __attribute__((address_space(3)))
; #define LDS_WAIT() asm volatile("s_waitcnt lgkmcnt(0)" ::: "memory")
; __device__ __forceinline__ unsigned pk2(float lo, float hi) { f32x2_t v = {lo, hi}; bf16x2_t b = __builtin_convertvector(v, bf16x2_t); return __builtin_bit_cast(unsigned, b); }
; template <int MAP> __device__ __forceinline__ int dest_row(int n) {
;     ...
;     if (MAP == 3) return n < 5120 ? n : (n < 5136 ? 15360 + (n - 5120) : n - 16);
;     if (MAP == 5) return n < 5120 ? n : (n < 5136 ? 15360 + (n - 5120) : n - 16);
; template <int MAP> __device__ __forceinline__ void p0_item(const float* W, int K, int N, bf16* WT, LAS float* scr, int item, int lane) {
;     ...
;     for (int i = 0; i < 32; ++i) { const int kk = 2 * i + (lane >> 5); scr[kk * 33 + (lane & 31)] = okr ? W[(size_t)(k0 + kk) * N + nn] : 0.f; }
;     LDS_WAIT(); asm volatile("" ::: "memory");
;     const int c = lane & 7;
; #pragma unroll
;     for (int j = 0; j < 4; ++j) { const int n = (lane >> 3) + 8 * j; const LAS float* s = scr + (8 * c) * 33 + n;
;         v4u o; o.x = pk2(s[0 * 33], s[1 * 33]); o.y = pk2(s[2 * 33], s[3 * 33]); o.z = pk2(s[4 * 33], s[5 * 33]); o.w = pk2(s[6 * 33], s[7 * 33]);
;         if (n0 + n < N && !(MAP == 3 && n0 + n >= 9232)) __builtin_nontemporal_store(o, (GAS v4u*)(WT + (size_t)dest_row<MAP>(n0 + n) * K + k0 + 8 * c)); }
.Lp5_skip:
	s_mov_b64 exec, s[30:31]
	v_add_u32_e32 v11, v13, v30
	s_waitcnt vmcnt(30)
	ds_write2_b32 v11, v18, v19 offset1:66
	v_add_u32_e32 v11, v13, v33
	s_waitcnt vmcnt(28)
	ds_write2_b32 v11, v20, v21 offset1:66
	v_add_u32_e32 v11, v13, v36
	s_waitcnt vmcnt(26)
	ds_write2_b32 v11, v22, v23 offset1:66
	v_add_u32_e32 v11, v13, v39
	s_waitcnt vmcnt(24)
	ds_write2_b32 v11, v24, v25 offset1:66
	v_add_u32_e32 v11, v13, v42
	s_waitcnt vmcnt(22)
	ds_write2_b32 v11, v26, v27 offset1:66
	v_add_u32_e32 v11, v13, v45
	s_waitcnt vmcnt(20)
	ds_write2_b32 v11, v28, v29 offset1:66
	v_add_u32_e32 v11, v13, v48
	s_waitcnt vmcnt(18)
	ds_write2_b32 v11, v97, v98 offset1:66
	v_add_u32_e32 v11, v13, v51
	s_waitcnt vmcnt(16)
	ds_write2_b32 v11, v99, v100 offset1:66
	v_add_u32_e32 v11, v13, v54
	s_waitcnt vmcnt(14)
	ds_write2_b32 v11, v101, v102 offset1:66
	v_add_u32_e32 v11, v13, v57
	s_waitcnt vmcnt(12)
	ds_write2_b32 v11, v103, v104 offset1:66
	v_add_u32_e32 v11, v13, v58
	s_waitcnt vmcnt(10)
	ds_write2_b32 v11, v105, v106 offset1:66
	v_add_u32_e32 v11, v13, v59
	s_waitcnt vmcnt(8)
	ds_write2_b32 v11, v107, v108 offset1:66
	v_add_u32_e32 v11, v13, v60
	s_waitcnt vmcnt(6)
	ds_write2_b32 v11, v109, v110 offset1:66
	v_add_u32_e32 v11, v13, v60
	s_waitcnt vmcnt(4)
	ds_write2_b32 v11, v111, v112 offset0:132 offset1:198
	v_add_u32_e32 v11, v13, v60
	v_add_u32_e32 v11, 0x400, v11
	s_waitcnt vmcnt(2)
	ds_write2_b32 v11, v113, v114 offset0:8 offset1:74
	v_add_u32_e32 v11, v13, v60
	v_add_u32_e32 v11, 0x400, v11
	s_waitcnt vmcnt(0)
	ds_write2_b32 v11, v115, v116 offset0:140 offset1:206
	s_waitcnt lgkmcnt(0)
	ds_read2_b32 v[22:23], v62 offset0:198 offset1:231
	ds_read2_b32 v[20:21], v62 offset0:132 offset1:165
	ds_read2_b32 v[18:19], v62 offset0:66 offset1:99
	ds_read2_b32 v[16:17], v62 offset1:33
	s_and_b32 s12, 0xffff, s12
	s_cmpk_lt_u32 s12, 0xa0
	v_or_b32_e32 v11, s10, v61
	s_cselect_b64 s[40:41], -1, 0
	s_cmpk_gt_u32 s12, 0x9f
	s_cselect_b64 s[30:31], -1, 0
	s_and_b64 vcc, exec, s[40:41]
	v_mov_b32_e32 v24, v11
	s_cbranch_vccnz .LBB0_173
	s_cmpk_lg_i32 s12, 0xa0
	s_mov_b64 s[34:35], -1
	s_cbranch_scc0 .LBB0_171
	v_add_u32_e32 v24, -16, v11
	s_mov_b64 s[34:35], 0

; __device__ __forceinline__ unsigned xb_ld(unsigned* p)              { return __hip_atomic_load(p, __ATOMIC_RELAXED, __HIP_MEMORY_SCOPE_AGENT); }
; __device__ __forceinline__ void xcd_barrier_complete(unsigned* bar, unsigned x, unsigned& nloc, unsigned& nx) {
;     const unsigned G = gridDim.x * gridDim.y * gridDim.z;
;     unsigned sum, cnt, mine, sp = 0u;
;     for (;;) {
;         sum = 0u; cnt = 0u; mine = 0u;
; #pragma unroll
;         for (unsigned j = 0; j < 16; ++j) { const unsigned c = xb_ld(&bar[XB_XCNT(j)]); sum += c; cnt += (c > 0u) ? 1u : 0u; mine = (j == x) ? c : mine; }
;         if (sum == G) break;
;         __builtin_amdgcn_s_sleep(1);
;         if ((++sp & 255u) == 0u) { if (xb_ld(&bar[XB_TMO])) break; if (sp > XB_SPIN_CAP) { atomicAdd(&bar[XB_TMO], 1u); break; } }
;     }
.LBB0_350:
	v_readlane_b32 s2, v254, 11
	v_readlane_b32 s3, v254, 12
	s_mov_b64 s[14:15], -1
	s_nop 3
	global_load_dword v1, v17, s[2:3] sc1
	v_readlane_b32 s2, v254, 13
	v_readlane_b32 s3, v254, 14
	s_nop 4
	global_load_dword v2, v17, s[2:3] sc1
	v_readlane_b32 s2, v254, 15
	v_readlane_b32 s3, v254, 16
	s_nop 1
	s_nop 2
	global_load_dword v3, v17, s[2:3] sc1
	v_readlane_b32 s2, v254, 17
	v_readlane_b32 s3, v254, 18
	s_nop 1
	s_nop 2
	global_load_dword v4, v17, s[2:3] sc1
	v_readlane_b32 s2, v254, 19
	v_readlane_b32 s3, v254, 20
	s_nop 1
	s_nop 2
	global_load_dword v5, v17, s[2:3] sc1
	v_readlane_b32 s2, v254, 21
	v_readlane_b32 s3, v254, 22
	s_nop 1
	s_nop 2
	global_load_dword v6, v17, s[2:3] sc1
	v_readlane_b32 s2, v254, 23
	v_readlane_b32 s3, v254, 24
	s_nop 1
	s_nop 2
	global_load_dword v7, v17, s[2:3] sc1
	v_readlane_b32 s2, v254, 25
	v_readlane_b32 s3, v254, 26
	s_nop 1
	s_nop 2
	global_load_dword v8, v17, s[2:3] sc1
	v_readlane_b32 s2, v254, 27
	v_readlane_b32 s3, v254, 28
	s_nop 1
	s_nop 2
	global_load_dword v9, v17, s[2:3] sc1
	v_readlane_b32 s2, v254, 29
	v_readlane_b32 s3, v254, 30
	s_nop 1
	s_nop 2
	global_load_dword v10, v17, s[2:3] sc1
	v_readlane_b32 s2, v254, 31
	v_readlane_b32 s3, v254, 32
	s_nop 1
	s_nop 2
	global_load_dword v11, v17, s[2:3] sc1
	v_readlane_b32 s2, v254, 33
	v_readlane_b32 s3, v254, 34
	s_nop 1
	s_nop 2
	global_load_dword v12, v17, s[2:3] sc1
	v_readlane_b32 s2, v254, 35
	v_readlane_b32 s3, v254, 36
	s_nop 1
	s_nop 2
	global_load_dword v13, v17, s[2:3] sc1
	v_readlane_b32 s2, v254, 37
	v_readlane_b32 s3, v254, 38
	s_nop 1
	s_nop 2
	global_load_dword v14, v17, s[2:3] sc1
	v_readlane_b32 s2, v254, 39
	v_readlane_b32 s3, v254, 40
	s_nop 1
	s_nop 2
	global_load_dword v15, v17, s[2:3] sc1
	v_readlane_b32 s2, v254, 41
	v_readlane_b32 s3, v254, 42
	s_nop 1
	s_nop 2
	global_load_dword v16, v17, s[2:3] sc1
	s_mov_b64 s[2:3], -1
	s_nop 1
	s_waitcnt vmcnt(0)
	v_add_u32_e32 v18, v2, v1
	v_add_u32_e32 v18, v18, v3
	v_add_u32_e32 v18, v18, v4
	v_add_u32_e32 v18, v18, v5
	v_add_u32_e32 v18, v18, v6
	v_add_u32_e32 v18, v18, v7
	v_add_u32_e32 v18, v18, v8
	v_add_u32_e32 v18, v18, v9
	v_add_u32_e32 v18, v18, v10
	v_add_u32_e32 v18, v18, v11
	v_add_u32_e32 v18, v18, v12
	v_add_u32_e32 v18, v18, v13
	v_add_u32_e32 v18, v18, v14
	v_add_u32_e32 v18, v18, v15
	v_add_u32_e32 v18, v18, v16
	v_cmp_eq_u32_e32 vcc, s4, v18
	s_cbranch_vccnz .LBB0_349
	s_and_b32 s2, s5, 0xff
	s_cmp_eq_u32 s2, 0
	s_mov_b64 s[2:3], -1
	s_mov_b64 s[18:19], -1
	s_sleep 1
	s_cbranch_scc1 .LBB0_354
	s_and_b64 vcc, exec, s[18:19]
	s_cbranch_vccz .LBB0_349
